# v035 + NA: removed value-no-op negm copies (24/iter), canonicalizing max, nops between max3
# speedup vs baseline: 1.0063x; 1.0040x over previous
; template <bool NA>
; __device__ __forceinline__ void attn_unit(LAS unsigned char* lds, const bf16_t* Q, const bf16_t* Kg, const bf16_t* Kr, const bf16_t* Vt, bf16_t* O,
;                                           int h, int seqrow0, int q0, int t0, int NT, int rows, int g0, const float* rpb_h, int wid) {
;     ...
;     f32x16 sA0, sA1, sB0, sB1; float tmA, tmB;
;     A_QK(sA0, sA1, 0);
;     A_MASK(sA0, sA1, 0);
;     tmA = rowmax32(sA0, sA1);
.LBB0_733:
	v_lshlrev_b32_e32 v0, 4, v4
	v_mul_u32_u24_e32 v2, 0x90, v3
	v_add3_u32 v173, v0, v2, 0
	s_waitcnt vmcnt(0)
	s_waitcnt lgkmcnt(0)
	s_barrier
	ds_read_b128 v[6:9], v173
	ds_read_b128 v[10:13], v173 offset:32
	s_waitcnt vmcnt(3) lgkmcnt(1)
	v_mfma_f32_32x32x16_bf16 v[44:59], v[6:9], v[146:149], 0
	s_cmp_gt_i32 s81, -1
	s_cselect_b64 s[38:39], -1, 0
	s_add_i32 s10, s10, s84
	v_sub_co_u32_e64 v2, s[6:7], s10, 4
	s_nop 0
	v_readfirstlane_b32 s8, v2
	s_min_u32 s1, s8, s1
	s_waitcnt vmcnt(2) lgkmcnt(0)
	v_mfma_f32_32x32x16_bf16 v[44:59], v[10:13], v[150:153], v[44:59]
	ds_read_b128 v[6:9], v173 offset:4608
	ds_read_b128 v[10:13], v173 offset:4640
	s_and_b64 s[6:7], s[6:7], exec
	s_cselect_b32 s33, 0, s1
	s_cmp_ge_u32 s79, s33
	s_cselect_b64 s[6:7], -1, 0
	s_add_i32 s88, s33, 8
	v_readlane_b32 s1, v244, 28
	s_waitcnt lgkmcnt(1)
	v_mfma_f32_32x32x16_bf16 v[28:43], v[6:9], v[146:149], 0
	s_cmp_lt_u32 s79, s88
	v_or_b32_e32 v5, s1, v3
	s_cselect_b64 s[8:9], -1, 0
	s_sub_i32 s1, s79, s10
	s_and_b64 s[6:7], s[6:7], s[8:9]
	s_mul_i32 s1, s1, 31
	s_addk_i32 s1, 0xe8
	s_waitcnt lgkmcnt(0)
	v_mfma_f32_32x32x16_bf16 v[28:43], v[10:13], v[150:153], v[28:43]
	ds_read_b128 v[6:9], v173 offset:64
	ds_read_b128 v[10:13], v173 offset:96
	s_and_b64 vcc, s[38:39], s[6:7]
	s_and_b64 s[6:7], vcc, exec
	s_cselect_b32 s1, s1, 15
	v_med3_u32 v2, v5, 8, 56
	v_sub_u32_e32 v5, s1, v5
	v_lshlrev_b32_e32 v5, 2, v5
	s_waitcnt vmcnt(1) lgkmcnt(1)
	v_mfma_f32_32x32x16_bf16 v[44:59], v[6:9], v[154:157], v[44:59]
	ds_read_b128 v[6:9], v173 offset:4672
	ds_read_b128 v[14:17], v173 offset:4704
	s_add_i32 s1, 0, 0x16400
	v_lshlrev_b32_e32 v172, 2, v4
	v_sub_u32_e32 v2, v172, v2
	v_add_u32_e32 v2, 8, v2
	v_cndmask_b32_e32 v4, v176, v2, vcc
	v_cmp_gt_u32_e32 vcc, 16, v4
	s_waitcnt lgkmcnt(1)
	v_mfma_f32_32x32x16_bf16 v[28:43], v[6:9], v[154:157], v[28:43]
	v_add3_u32 v6, s1, v5, v0
	ds_read_b32 v5, v6 offset:128
	s_waitcnt vmcnt(0)
	v_mfma_f32_32x32x16_bf16 v[44:59], v[10:13], v[158:161], v[44:59]
	s_waitcnt lgkmcnt(1)
	v_mfma_f32_32x32x16_bf16 v[28:43], v[14:17], v[158:161], v[28:43]
	v_mov_b32_e32 v17, 0xff800000
	v_mov_b32_e32 v16, 0xff800000
	ds_read_b32 v16, v6
	ds_read_b32 v17, v6 offset:4
	ds_read_b32 v18, v6 offset:8
	ds_read_b32 v19, v6 offset:12
	ds_read_b32 v20, v6 offset:32
	ds_read_b32 v21, v6 offset:36
	ds_read_b32 v22, v6 offset:40
	ds_read_b32 v23, v6 offset:44
	ds_read_b32 v24, v6 offset:64
	ds_read_b32 v25, v6 offset:68
	ds_read_b32 v26, v6 offset:72
	ds_read_b32 v27, v6 offset:76
	ds_read_b32 v60, v6 offset:96
	ds_read_b32 v61, v6 offset:100
	ds_read_b32 v62, v6 offset:104
	ds_read_b32 v63, v6 offset:108
	s_waitcnt lgkmcnt(0)
	v_cmp_gt_u32_e32 vcc, 16, v4
	v_add_f32_e32 v16, v44, v16
	v_add_u32_e32 v207, 1, v4
	v_cndmask_b32_e32 v16, v177, v16, vcc
	v_cmp_gt_u32_e32 vcc, 16, v207
	v_add_f32_e32 v17, v45, v17
	v_add_u32_e32 v207, 2, v4
	v_cndmask_b32_e32 v17, v177, v17, vcc
	v_cmp_gt_u32_e32 vcc, 16, v207
	v_add_f32_e32 v18, v46, v18
	v_add_u32_e32 v207, 3, v4
	v_cndmask_b32_e32 v18, v177, v18, vcc
	v_cmp_gt_u32_e32 vcc, 16, v207
	v_add_f32_e32 v19, v47, v19
	v_add_u32_e32 v207, 8, v4
	v_cndmask_b32_e32 v19, v177, v19, vcc
	v_cmp_gt_u32_e32 vcc, 16, v207
	v_add_f32_e32 v20, v48, v20
	v_add_u32_e32 v207, 9, v4
	v_cndmask_b32_e32 v20, v177, v20, vcc
	v_cmp_gt_u32_e32 vcc, 16, v207
	v_add_f32_e32 v21, v49, v21
	v_add_u32_e32 v207, 10, v4
	v_cndmask_b32_e32 v21, v177, v21, vcc
	v_cmp_gt_u32_e32 vcc, 16, v207
	v_add_f32_e32 v22, v50, v22
	v_add_u32_e32 v207, 11, v4
	v_cndmask_b32_e32 v22, v177, v22, vcc
	v_cmp_gt_u32_e32 vcc, 16, v207
	v_add_f32_e32 v23, v51, v23
	s_nop 0
	v_cndmask_b32_e32 v23, v177, v23, vcc
	v_cmp_lt_u32_e32 vcc, s40, v4
	v_add_f32_e32 v24, v52, v24
	v_add_u32_e32 v207, 17, v4
	v_cndmask_b32_e32 v24, v177, v24, vcc
	v_cmp_gt_u32_e32 vcc, 16, v207
	v_add_f32_e32 v25, v53, v25
	v_add_u32_e32 v207, 18, v4
	v_cndmask_b32_e32 v25, v177, v25, vcc
	v_cmp_gt_u32_e32 vcc, 16, v207
	v_add_f32_e32 v26, v54, v26
	v_add_u32_e32 v207, 19, v4
	v_cndmask_b32_e32 v26, v177, v26, vcc
	v_cmp_gt_u32_e32 vcc, 16, v207
	v_add_f32_e32 v27, v55, v27
	v_add_u32_e32 v207, 24, v4
	v_cndmask_b32_e32 v27, v177, v27, vcc
	v_cmp_gt_u32_e32 vcc, 16, v207
	v_add_f32_e32 v60, v56, v60
	v_add_u32_e32 v207, 25, v4
	v_cndmask_b32_e32 v60, v177, v60, vcc
	v_cmp_gt_u32_e32 vcc, 16, v207
	v_add_f32_e32 v61, v57, v61
	v_add_u32_e32 v207, 26, v4
	v_cndmask_b32_e32 v61, v177, v61, vcc
	v_cmp_gt_u32_e32 vcc, 16, v207
	v_add_f32_e32 v62, v58, v62
	v_add_u32_e32 v207, 27, v4
	v_cndmask_b32_e32 v62, v177, v62, vcc
	v_cmp_gt_u32_e32 vcc, 16, v207
	v_add_f32_e32 v63, v59, v63
	s_nop 0
	v_cndmask_b32_e32 v63, v177, v63, vcc
	ds_read_b32 v7, v6 offset:132
	ds_read_b32 v8, v6 offset:136
	ds_read_b32 v9, v6 offset:140
	ds_read_b32 v10, v6 offset:160
	ds_read_b32 v11, v6 offset:164
	ds_read_b32 v12, v6 offset:168
	ds_read_b32 v13, v6 offset:172
	ds_read_b32 v14, v6 offset:192
	ds_read_b32 v15, v6 offset:196
	ds_read_b32 v44, v6 offset:200
	ds_read_b32 v45, v6 offset:204
	ds_read_b32 v46, v6 offset:224
	ds_read_b32 v47, v6 offset:228
	ds_read_b32 v48, v6 offset:232
	ds_read_b32 v49, v6 offset:236
	s_waitcnt lgkmcnt(14)
	v_add_f32_e32 v6, v29, v7
	s_waitcnt lgkmcnt(13)
	v_add_f32_e32 v7, v30, v8
	s_waitcnt lgkmcnt(12)
	v_add_f32_e32 v8, v31, v9
	s_waitcnt lgkmcnt(11)
	v_add_f32_e32 v9, v32, v10
	s_waitcnt lgkmcnt(10)
; #define LAS __attribute__((address_space(3)))
; __device__ __forceinline__ float max3f(float a, float b, float c) { float r; asm("v_max3_f32 %0, %1, %2, %3" : "=v"(r) : "v"(a), "v"(b), "v"(c)); return r; }
; __device__ __forceinline__ float rowmax32(const f32x16& p0, const f32x16& p1) {
;     float a = max3f(p0[0], p0[1], p1[0]), b = max3f(p0[2], p0[3], p1[1]); a = max3f(a, p1[2], p1[3]);
; #pragma unroll
;     for (int r = 4; r < 16; r += 4) { a = max3f(a, p0[r], p0[r + 1]); b = max3f(b, p0[r + 2], p0[r + 3]); a = max3f(a, p1[r], p1[r + 1]); b = max3f(b, p1[r + 2], p1[r + 3]); }
;     const float m = fmaxf(a, b);
;     auto rr = __builtin_amdgcn_permlane32_swap(__float_as_uint(m), __float_as_uint(m), false, false);
;     return fmaxf(__uint_as_float(rr[0]), __uint_as_float(rr[1]));
; }
; template <bool NA>
; __device__ __forceinline__ void attn_unit(LAS unsigned char* lds, const bf16_t* Q, const bf16_t* Kg, const bf16_t* Kr, const bf16_t* Vt, bf16_t* O,
;                                           int h, int seqrow0, int q0, int t0, int NT, int rows, int g0, const float* rpb_h, int wid) {
;     ...
;     f32x16 o0, o1, negm;
; #pragma unroll
;     for (int r = 0; r < 16; ++r) { o0[r] = 0.f; o1[r] = 0.f; negm[r] = 0.f; }
;     float mref = 0.f, lrun = 0.f;
;     const LAS unsigned char* kfb = lds + A_K0 + (r32 * KP + 8 * hi) * 2;
;     const LAS unsigned char* vfb = lds + A_V0 + (r32 * 72 + 8 * hi) * 2;
	v_add_f32_e32 v10, v33, v11
	v_add_u32_e32 v33, 33, v4
	v_cmp_gt_u32_e32 vcc, 16, v33
	v_add_u32_e32 v33, 34, v4
	v_cmp_gt_u32_e64 s[6:7], 16, v33
	v_add_u32_e32 v33, 35, v4
	v_cmp_gt_u32_e64 s[8:9], 16, v33
	v_add_u32_e32 v33, 40, v4
	v_cmp_gt_u32_e64 s[10:11], 16, v33
	v_add_u32_e32 v33, 41, v4
	v_cmp_gt_u32_e64 s[12:13], 16, v33
	v_add_u32_e32 v33, 42, v4
	v_cmp_gt_u32_e64 s[14:15], 16, v33
	v_add_u32_e32 v33, 43, v4
	v_cmp_gt_u32_e64 s[16:17], 16, v33
	v_add_u32_e32 v33, 49, v4
	v_cmp_gt_u32_e64 s[18:19], 16, v33
	v_add_u32_e32 v33, 50, v4
	v_cmp_gt_u32_e64 s[20:21], 16, v33
	v_add_u32_e32 v33, 51, v4
	v_cmp_gt_u32_e64 s[22:23], 16, v33
	v_add_u32_e32 v33, 56, v4
	v_cmp_gt_u32_e64 s[24:25], 16, v33
	v_add_u32_e32 v33, 57, v4
	v_cmp_gt_u32_e64 s[26:27], 16, v33
	v_add_u32_e32 v33, 58, v4
	v_cmp_gt_u32_e64 s[28:29], 16, v33
	v_add_u32_e32 v33, 59, v4
	v_and_b32_e32 v4, -16, v4
	v_add_f32_e32 v5, v28, v5
	v_cmp_eq_u32_e64 s[36:37], s41, v4
	v_cmp_eq_u32_e64 s[34:35], s42, v4
	v_cndmask_b32_e64 v82, v177, v7, s[6:7]
	v_cndmask_b32_e64 v80, v177, v5, s[36:37]
	v_max3_f32 v4, v16, v17, v80
	v_cndmask_b32_e64 v81, v177, v8, s[8:9]
	v_max3_f32 v4, v4, v82, v81
	v_cndmask_b32_e32 v95, v177, v6, vcc
	v_max3_f32 v5, v18, v19, v95
	s_waitcnt lgkmcnt(9)
	v_add_f32_e32 v11, v34, v12
	s_waitcnt lgkmcnt(8)
	v_add_f32_e32 v12, v35, v13
	v_max3_f32 v4, v4, v20, v21
	v_max3_f32 v5, v5, v22, v23
	v_cndmask_b32_e64 v84, v177, v9, s[10:11]
	v_cndmask_b32_e64 v89, v177, v10, s[12:13]
	v_max3_f32 v4, v4, v84, v89
	v_cndmask_b32_e64 v86, v177, v11, s[14:15]
	v_cndmask_b32_e64 v83, v177, v12, s[16:17]
	v_max3_f32 v5, v5, v86, v83
	s_waitcnt lgkmcnt(7)
	v_add_f32_e32 v13, v36, v14
	s_waitcnt lgkmcnt(6)
	v_add_f32_e32 v14, v37, v15
	s_waitcnt lgkmcnt(5)
	v_add_f32_e32 v15, v38, v44
	s_waitcnt lgkmcnt(4)
	v_add_f32_e32 v28, v39, v45
	v_max3_f32 v4, v4, v24, v25
	v_max3_f32 v5, v5, v26, v27
	v_cndmask_b32_e64 v88, v177, v13, s[34:35]
	v_cndmask_b32_e64 v91, v177, v14, s[18:19]
	v_max3_f32 v4, v4, v88, v91
	v_cndmask_b32_e64 v90, v177, v15, s[20:21]
	v_cndmask_b32_e64 v85, v177, v28, s[22:23]
	v_max3_f32 v5, v5, v90, v85
	s_waitcnt lgkmcnt(3)
	v_add_f32_e32 v29, v40, v46
	s_waitcnt lgkmcnt(2)
	v_add_f32_e32 v30, v41, v47
	s_waitcnt lgkmcnt(1)
	v_add_f32_e32 v31, v42, v48
	s_waitcnt lgkmcnt(0)
	v_add_f32_e32 v32, v43, v49
	v_cmp_gt_u32_e64 s[30:31], 16, v33
	v_max3_f32 v4, v4, v60, v61
	v_max3_f32 v5, v5, v62, v63
	v_cndmask_b32_e64 v92, v177, v29, s[24:25]
	v_cndmask_b32_e64 v93, v177, v30, s[26:27]
	v_max3_f32 v4, v4, v92, v93
	v_cndmask_b32_e64 v94, v177, v31, s[28:29]
	v_cndmask_b32_e64 v87, v177, v32, s[30:31]
	v_max3_f32 v5, v5, v94, v87
	v_max_f32_e32 v4, v4, v5
	v_mov_b32_e32 v5, v4
	s_nop 1
	v_permlane32_swap_b32_e32 v4, v5
	s_and_b64 vcc, exec, s[38:39]
	s_barrier
	s_cbranch_vccz .LBB0_868
	v_max_f32_e32 v180, v4, v5
	v_and_b32_e32 v4, -16, v2
	s_movk_i32 s1, 0xffef
	v_cmp_eq_u32_e64 s[8:9], s41, v4
	v_add_u32_e32 v5, 1, v2
	v_cmp_lt_u32_e64 s[40:41], s1, v2
	s_movk_i32 s1, 0xffd0
	v_cmp_gt_u32_e64 s[10:11], 16, v5
	v_add_u32_e32 v5, 33, v2
	v_cmp_eq_u32_e64 s[42:43], s1, v4
	v_add_u32_e32 v4, 17, v2
	v_cmp_gt_u32_e64 s[12:13], 16, v5
	v_add_u32_e32 v5, 2, v2
	v_cmp_gt_u32_e64 s[44:45], 16, v4
	v_add_u32_e32 v4, 49, v2
	v_cmp_gt_u32_e64 s[14:15], 16, v5
	v_add_u32_e32 v5, 34, v2
	v_cmp_gt_u32_e64 s[46:47], 16, v4
	v_add_u32_e32 v4, 18, v2
	v_cmp_gt_u32_e64 s[16:17], 16, v5
	v_add_u32_e32 v5, 3, v2
	v_cmp_gt_u32_e64 s[48:49], 16, v4
	v_add_u32_e32 v4, 50, v2
	v_cmp_gt_u32_e64 s[18:19], 16, v5
	v_add_u32_e32 v5, 35, v2
	v_cmp_gt_u32_e64 s[50:51], 16, v4
	v_add_u32_e32 v4, 19, v2
	v_cmp_gt_u32_e64 s[20:21], 16, v5
	v_add_u32_e32 v5, 8, v2
	v_cmp_gt_u32_e64 s[52:53], 16, v4
	v_add_u32_e32 v4, 51, v2
	v_cmp_gt_u32_e64 s[22:23], 16, v5
	v_add_u32_e32 v5, 40, v2
	v_cmp_gt_u32_e64 s[54:55], 16, v4
	v_add_u32_e32 v4, 24, v2
	v_cmp_gt_u32_e64 s[24:25], 16, v5
	v_add_u32_e32 v5, 9, v2
	v_cmp_gt_u32_e64 s[56:57], 16, v4
	v_add_u32_e32 v4, 56, v2
	v_cmp_gt_u32_e64 s[26:27], 16, v5
	v_add_u32_e32 v5, 41, v2
	v_cmp_gt_u32_e64 s[58:59], 16, v4
	v_add_u32_e32 v4, 25, v2
	v_cmp_gt_u32_e64 s[28:29], 16, v5
	v_add_u32_e32 v5, 10, v2
	v_cmp_gt_u32_e64 s[60:61], 16, v4
	v_add_u32_e32 v4, 57, v2
	v_cmp_gt_u32_e64 s[30:31], 16, v5
	v_add_u32_e32 v5, 42, v2
	v_cmp_gt_u32_e64 s[62:63], 16, v4
	v_add_u32_e32 v4, 26, v2
	v_cmp_gt_u32_e64 s[34:35], 16, v5
	v_add_u32_e32 v5, 11, v2
	v_cmp_gt_u32_e64 s[64:65], 16, v4
	v_add_u32_e32 v4, 58, v2
	v_cmp_gt_u32_e64 s[6:7], 16, v2
	v_cmp_gt_u32_e64 s[36:37], 16, v5
	v_add_u32_e32 v5, 43, v2
	v_cmp_gt_u32_e64 s[66:67], 16, v4
	v_add_u32_e32 v4, 27, v2
	v_add_u32_e32 v2, 59, v2
	s_mul_i32 s1, s79, 0x7c
	v_cmp_gt_u32_e64 s[70:71], 16, v2
	v_add_u32_e32 v0, s1, v0
	v_lshlrev_b32_e32 v2, 2, v3
	v_sub_u32_e32 v0, v0, v2
	s_mulk_i32 s0, 0x1f0
	v_subrev_u32_e32 v0, s0, v0
	v_readlane_b32 s0, v244, 29
	v_mov_b32_e32 v14, v1
	v_mov_b32_e32 v15, v1
	v_cmp_gt_u32_e64 s[38:39], 16, v5
	v_cmp_gt_u32_e64 s[68:69], 16, v4
	v_add_u32_e32 v179, s0, v0
	v_mov_b32_e32 v0, v1
	v_mov_b32_e32 v2, v1
	v_mov_b32_e32 v3, v1
	v_mov_b32_e32 v4, v1
	v_mov_b32_e32 v5, v1
	v_mov_b32_e32 v6, v1
	v_mov_b32_e32 v7, v1
	v_mov_b32_e32 v8, v1
	v_mov_b32_e32 v9, v1
	v_mov_b32_e32 v10, v1
	v_mov_b32_e32 v11, v1
	v_mov_b32_e32 v12, v1
	v_mov_b32_e32 v13, v1
	v_mov_b32_e32 v178, 0
	v_mov_b64_e32 v[58:59], v[14:15]
	v_mov_b64_e32 v[42:43], v[14:15]
	s_sub_i32 s83, s79, s33
	s_mov_b32 s1, 4
	v_mov_b64_e32 v[56:57], v[12:13]
	v_mov_b64_e32 v[54:55], v[10:11]
	v_mov_b64_e32 v[52:53], v[8:9]
	v_mov_b64_e32 v[50:51], v[6:7]
	v_mov_b64_e32 v[48:49], v[4:5]
	v_mov_b64_e32 v[46:47], v[2:3]
	v_mov_b64_e32 v[44:45], v[0:1]
	v_mov_b64_e32 v[40:41], v[12:13]
	v_mov_b64_e32 v[38:39], v[10:11]
	v_mov_b64_e32 v[36:37], v[8:9]
	v_mov_b64_e32 v[34:35], v[6:7]
	v_mov_b64_e32 v[32:33], v[4:5]
	v_mov_b64_e32 v[30:31], v[2:3]
	v_mov_b64_e32 v[28:29], v[0:1]
	v_mov_b32_e32 v2, 0
	v_mov_b32_e32 v112, 0
	v_mov_b32_e32 v113, v178
	v_mov_b32_e32 v114, v178
	v_mov_b32_e32 v115, v178
	v_mov_b32_e32 v116, v178
	v_mov_b32_e32 v117, v178
	v_mov_b32_e32 v118, v178
	v_mov_b32_e32 v119, v178
	v_mov_b32_e32 v120, v178
	v_mov_b32_e32 v121, v178
	v_mov_b32_e32 v122, v178
	v_mov_b32_e32 v123, v178
	v_mov_b32_e32 v124, v178
	v_mov_b32_e32 v125, v178
	v_mov_b32_e32 v126, v178
	v_mov_b32_e32 v127, v178
	s_branch .LBB0_768

; __device__ __forceinline__ float max3f(float a, float b, float c) { float r; asm("v_max3_f32 %0, %1, %2, %3" : "=v"(r) : "v"(a), "v"(b), "v"(c)); return r; }
; __device__ __forceinline__ float rowmax32(const f32x16& p0, const f32x16& p1) {
;     float a = max3f(p0[0], p0[1], p1[0]), b = max3f(p0[2], p0[3], p1[1]); a = max3f(a, p1[2], p1[3]);
; #pragma unroll
;     for (int r = 4; r < 16; r += 4) { a = max3f(a, p0[r], p0[r + 1]); b = max3f(b, p0[r + 2], p0[r + 3]); a = max3f(a, p1[r], p1[r + 1]); b = max3f(b, p1[r + 2], p1[r + 3]); }
;     const float m = fmaxf(a, b);
;     auto rr = __builtin_amdgcn_permlane32_swap(__float_as_uint(m), __float_as_uint(m), false, false);
;     return fmaxf(__uint_as_float(rr[0]), __uint_as_float(rr[1]));
; }
.LBB0_782:
	s_add_i32 s87, s1, -4
	s_add_i32 s0, s74, -3
	s_cmp_ge_i32 s0, s33
	s_cselect_b64 s[94:95], -1, 0
	s_cmp_lt_i32 s0, s88
	s_cselect_b64 s[96:97], -1, 0
	s_and_b64 s[94:95], s[94:95], s[96:97]
	s_add_i32 s0, s1, -3
	s_cmp_lt_i32 s87, s81
	s_cselect_b64 s[96:97], -1, 0
	s_and_b64 vcc, s[94:95], s[96:97]
	s_andn2_b64 vcc, exec, vcc
	s_cbranch_vccnz .LBB0_817
	s_and_b32 s90, s0, 3
	s_mulk_i32 s90, 0x3400
	v_add_u32_e32 v0, s90, v173
	ds_read_b128 v[64:67], v0 offset:4608
	ds_read_b128 v[68:71], v0
	ds_read_b128 v[72:75], v0 offset:32
	ds_read_b128 v[220:223], v0 offset:4640
	ds_read_b128 v[224:227], v0 offset:64
	ds_read_b128 v[228:231], v0 offset:4672
	ds_read_b128 v[232:235], v0 offset:96
	ds_read_b128 v[236:239], v0 offset:4704
	s_waitcnt lgkmcnt(7)
	v_mfma_f32_32x32x16_bf16 v[96:111], v[64:67], v[146:149], v[112:127]
	s_waitcnt lgkmcnt(6)
	v_mfma_f32_32x32x16_bf16 v[130:145], v[68:71], v[146:149], v[112:127]
	s_waitcnt lgkmcnt(5)
	v_mfma_f32_32x32x16_bf16 v[130:145], v[72:75], v[150:153], v[130:145]
	s_waitcnt lgkmcnt(4)
	v_mfma_f32_32x32x16_bf16 v[96:111], v[220:223], v[150:153], v[96:111]
	s_waitcnt lgkmcnt(3)
	v_mfma_f32_32x32x16_bf16 v[130:145], v[224:227], v[154:157], v[130:145]
	s_waitcnt lgkmcnt(2)
	v_mfma_f32_32x32x16_bf16 v[96:111], v[228:231], v[154:157], v[96:111]
	s_waitcnt lgkmcnt(1)
	v_mfma_f32_32x32x16_bf16 v[130:145], v[232:235], v[158:161], v[130:145]
	s_waitcnt lgkmcnt(0)
	v_mfma_f32_32x32x16_bf16 v[96:111], v[236:239], v[158:161], v[96:111]
	ds_read_b32 v0, v179 offset:128
	ds_read_b32 v64, v179
	ds_read_b32 v65, v179 offset:4
	ds_read_b32 v66, v179 offset:8
	ds_read_b32 v67, v179 offset:12
	ds_read_b32 v68, v179 offset:32
	ds_read_b32 v69, v179 offset:36
	ds_read_b32 v70, v179 offset:40
	ds_read_b32 v71, v179 offset:44
	ds_read_b32 v72, v179 offset:64
	ds_read_b32 v73, v179 offset:68
	ds_read_b32 v74, v179 offset:72
	ds_read_b32 v75, v179 offset:76
	ds_read_b32 v76, v179 offset:96
	ds_read_b32 v77, v179 offset:100
	ds_read_b32 v78, v179 offset:104
	ds_read_b32 v79, v179 offset:108
	s_waitcnt lgkmcnt(0)
	v_add_f32_e32 v64, v130, v64
	v_cndmask_b32_e64 v64, v177, v64, s[6:7]
	v_add_f32_e32 v65, v131, v65
	v_cndmask_b32_e64 v65, v177, v65, s[10:11]
	v_add_f32_e32 v66, v132, v66
	v_cndmask_b32_e64 v66, v177, v66, s[14:15]
	v_add_f32_e32 v67, v133, v67
	v_cndmask_b32_e64 v67, v177, v67, s[18:19]
	v_add_f32_e32 v68, v134, v68
	v_cndmask_b32_e64 v68, v177, v68, s[22:23]
	v_add_f32_e32 v69, v135, v69
	v_cndmask_b32_e64 v69, v177, v69, s[26:27]
	v_add_f32_e32 v70, v136, v70
	v_cndmask_b32_e64 v70, v177, v70, s[30:31]
	v_add_f32_e32 v71, v137, v71
	v_cndmask_b32_e64 v71, v177, v71, s[36:37]
	v_add_f32_e32 v72, v138, v72
	v_cndmask_b32_e64 v72, v177, v72, s[40:41]
	v_add_f32_e32 v73, v139, v73
	v_cndmask_b32_e64 v73, v177, v73, s[44:45]
	v_add_f32_e32 v74, v140, v74
	v_cndmask_b32_e64 v74, v177, v74, s[48:49]
	v_add_f32_e32 v75, v141, v75
	v_cndmask_b32_e64 v75, v177, v75, s[52:53]
	v_add_f32_e32 v76, v142, v76
	v_cndmask_b32_e64 v76, v177, v76, s[56:57]
	v_add_f32_e32 v77, v143, v77
	v_cndmask_b32_e64 v77, v177, v77, s[60:61]
	v_add_f32_e32 v78, v144, v78
	v_cndmask_b32_e64 v78, v177, v78, s[64:65]
	v_add_f32_e32 v79, v145, v79
	v_cndmask_b32_e64 v79, v177, v79, s[68:69]
	ds_read_b32 v3, v179 offset:132
	ds_read_b32 v129, v179 offset:136
	ds_read_b32 v130, v179 offset:140
	ds_read_b32 v131, v179 offset:160
	ds_read_b32 v132, v179 offset:164
	ds_read_b32 v133, v179 offset:168
	ds_read_b32 v134, v179 offset:172
	ds_read_b32 v135, v179 offset:192
	ds_read_b32 v136, v179 offset:196
	ds_read_b32 v137, v179 offset:200
	ds_read_b32 v138, v179 offset:204
	ds_read_b32 v139, v179 offset:224
	ds_read_b32 v140, v179 offset:228
	ds_read_b32 v142, v179 offset:232
	ds_read_b32 v141, v179 offset:236
	s_waitcnt lgkmcnt(14)
	v_add_f32_e32 v0, v96, v0
	v_cndmask_b32_e64 v96, v177, v0, s[8:9]
	v_add_f32_e32 v0, v97, v3
	v_cndmask_b32_e64 v97, v177, v0, s[12:13]
	s_waitcnt lgkmcnt(13)
	v_add_f32_e32 v0, v98, v129
	v_cndmask_b32_e64 v98, v177, v0, s[16:17]
	s_waitcnt lgkmcnt(12)
	v_add_f32_e32 v0, v99, v130
	v_cndmask_b32_e64 v99, v177, v0, s[20:21]
	s_waitcnt lgkmcnt(11)
	v_add_f32_e32 v0, v100, v131
	v_cndmask_b32_e64 v100, v177, v0, s[24:25]
	s_waitcnt lgkmcnt(10)
	v_add_f32_e32 v0, v101, v132
	v_cndmask_b32_e64 v101, v177, v0, s[28:29]
	s_waitcnt lgkmcnt(9)
	v_add_f32_e32 v0, v102, v133
	v_cndmask_b32_e64 v102, v177, v0, s[34:35]
	s_waitcnt lgkmcnt(8)
	v_add_f32_e32 v0, v103, v134
	v_cndmask_b32_e64 v103, v177, v0, s[38:39]
	s_waitcnt lgkmcnt(7)
	v_add_f32_e32 v0, v104, v135
	v_cndmask_b32_e64 v104, v177, v0, s[42:43]
	s_waitcnt lgkmcnt(6)
	v_add_f32_e32 v0, v105, v136
	v_cndmask_b32_e64 v105, v177, v0, s[46:47]
	s_waitcnt lgkmcnt(5)
	v_add_f32_e32 v0, v106, v137
	v_cndmask_b32_e64 v106, v177, v0, s[50:51]
	s_waitcnt lgkmcnt(4)
	v_add_f32_e32 v0, v107, v138
	v_cndmask_b32_e64 v107, v177, v0, s[54:55]
	s_waitcnt lgkmcnt(3)
	v_add_f32_e32 v0, v108, v139
	v_cndmask_b32_e64 v108, v177, v0, s[58:59]
	s_waitcnt lgkmcnt(2)
	v_add_f32_e32 v0, v109, v140
	v_cndmask_b32_e64 v109, v177, v0, s[62:63]
	s_waitcnt lgkmcnt(1)
	v_add_f32_e32 v0, v110, v142
	v_cndmask_b32_e64 v110, v177, v0, s[66:67]
	s_waitcnt lgkmcnt(0)
	v_add_f32_e32 v0, v111, v141
	v_cndmask_b32_e64 v111, v177, v0, s[70:71]
	v_max3_f32 v0, v64, v65, v96
	v_max3_f32 v3, v66, v67, v97
	v_max3_f32 v0, v0, v98, v99
	v_max3_f32 v3, v3, v70, v71
	v_max3_f32 v0, v0, v68, v69
	v_max3_f32 v3, v3, v102, v103
	v_max3_f32 v0, v0, v100, v101
	v_max3_f32 v3, v3, v74, v75
	v_max3_f32 v0, v0, v72, v73
	v_max3_f32 v3, v3, v106, v107
	v_max3_f32 v0, v0, v104, v105
	v_max3_f32 v3, v3, v78, v79
	v_max3_f32 v0, v0, v76, v77
	v_max3_f32 v3, v3, v110, v111
	v_max3_f32 v0, v0, v108, v109
	v_max_f32_e32 v0, v0, v3
	v_mov_b32_e32 v3, v0
	s_nop 1
	v_permlane32_swap_b32_e32 v0, v3
	v_max_f32_e32 v3, v0, v3
	s_and_b64 vcc, exec, s[72:73]
	s_cbranch_vccz .LBB0_818

; __device__ __forceinline__ float max3f(float a, float b, float c) { float r; asm("v_max3_f32 %0, %1, %2, %3" : "=v"(r) : "v"(a), "v"(b), "v"(c)); return r; }
; __device__ __forceinline__ float rowmax32(const f32x16& p0, const f32x16& p1) {
;     float a = max3f(p0[0], p0[1], p1[0]), b = max3f(p0[2], p0[3], p1[1]); a = max3f(a, p1[2], p1[3]);
; #pragma unroll
;     for (int r = 4; r < 16; r += 4) { a = max3f(a, p0[r], p0[r + 1]); b = max3f(b, p0[r + 2], p0[r + 3]); a = max3f(a, p1[r], p1[r + 1]); b = max3f(b, p1[r + 2], p1[r + 3]); }
;     const float m = fmaxf(a, b);
;     auto rr = __builtin_amdgcn_permlane32_swap(__float_as_uint(m), __float_as_uint(m), false, false);
;     return fmaxf(__uint_as_float(rr[0]), __uint_as_float(rr[1]));
; }
.LBB0_829:
	s_add_i32 s74, s74, -2
	s_cmp_ge_i32 s74, s33
	s_cselect_b64 s[90:91], -1, 0
	s_cmp_lt_i32 s74, s88
	s_cselect_b64 s[94:95], -1, 0
	s_and_b64 s[90:91], s[90:91], s[94:95]
	s_cmp_le_i32 s85, s81
	s_cselect_b64 s[94:95], -1, 0
	v_mov_b64_e32 v[144:145], v[126:127]
	s_and_b64 s[90:91], s[90:91], s[94:95]
	v_mov_b64_e32 v[142:143], v[124:125]
	v_mov_b64_e32 v[140:141], v[122:123]
	v_mov_b64_e32 v[138:139], v[120:121]
	v_mov_b64_e32 v[136:137], v[118:119]
	v_mov_b64_e32 v[134:135], v[116:117]
	v_mov_b64_e32 v[132:133], v[114:115]
	v_mov_b64_e32 v[130:131], v[112:113]
	s_andn2_b64 vcc, exec, s[90:91]
	s_cbranch_vccnz .LBB0_863
	s_mulk_i32 s77, 0x3400
	v_add_u32_e32 v0, s77, v173
	ds_read_b128 v[4:7], v0 offset:4608
	ds_read_b128 v[8:11], v0
	ds_read_b128 v[12:15], v0 offset:32
	ds_read_b128 v[220:223], v0 offset:4640
	ds_read_b128 v[224:227], v0 offset:64
	ds_read_b128 v[228:231], v0 offset:4672
	ds_read_b128 v[232:235], v0 offset:96
	ds_read_b128 v[236:239], v0 offset:4704
	v_mov_b32_e32 v17, 0xff800000
	v_mov_b32_e32 v16, 0xff800000
	s_waitcnt lgkmcnt(6)
	v_mfma_f32_32x32x16_bf16 v[80:95], v[8:11], v[146:149], v[130:145]
	v_mfma_f32_32x32x16_bf16 v[130:145], v[4:7], v[146:149], v[130:145]
	s_waitcnt lgkmcnt(5)
	v_mfma_f32_32x32x16_bf16 v[80:95], v[12:15], v[150:153], v[80:95]
	s_waitcnt lgkmcnt(4)
	v_mfma_f32_32x32x16_bf16 v[130:145], v[220:223], v[150:153], v[130:145]
	s_waitcnt lgkmcnt(3)
	v_mfma_f32_32x32x16_bf16 v[80:95], v[224:227], v[154:157], v[80:95]
	s_waitcnt lgkmcnt(2)
	v_mfma_f32_32x32x16_bf16 v[130:145], v[228:231], v[154:157], v[130:145]
	s_waitcnt lgkmcnt(1)
	v_mfma_f32_32x32x16_bf16 v[80:95], v[232:235], v[158:161], v[80:95]
	s_waitcnt lgkmcnt(0)
	v_mfma_f32_32x32x16_bf16 v[130:145], v[236:239], v[158:161], v[130:145]
	ds_read_b32 v0, v179 offset:252
	ds_read_b32 v16, v179 offset:124
	ds_read_b32 v17, v179 offset:128
	ds_read_b32 v18, v179 offset:132
	ds_read_b32 v19, v179 offset:136
	ds_read_b32 v20, v179 offset:156
	ds_read_b32 v21, v179 offset:160
	ds_read_b32 v22, v179 offset:164
	ds_read_b32 v23, v179 offset:168
	ds_read_b32 v24, v179 offset:188
	ds_read_b32 v25, v179 offset:192
	ds_read_b32 v26, v179 offset:196
	ds_read_b32 v27, v179 offset:200
	ds_read_b32 v60, v179 offset:220
	ds_read_b32 v61, v179 offset:224
	ds_read_b32 v62, v179 offset:228
	ds_read_b32 v63, v179 offset:232
	s_waitcnt lgkmcnt(0)
	v_add_f32_e32 v16, v80, v16
	v_cndmask_b32_e64 v16, v177, v16, s[6:7]
	v_add_f32_e32 v17, v81, v17
	v_cndmask_b32_e64 v17, v177, v17, s[10:11]
	v_add_f32_e32 v18, v82, v18
	v_cndmask_b32_e64 v18, v177, v18, s[14:15]
	v_add_f32_e32 v19, v83, v19
	v_cndmask_b32_e64 v19, v177, v19, s[18:19]
	v_add_f32_e32 v20, v84, v20
	v_cndmask_b32_e64 v20, v177, v20, s[22:23]
	v_add_f32_e32 v21, v85, v21
	v_cndmask_b32_e64 v21, v177, v21, s[26:27]
	v_add_f32_e32 v22, v86, v22
	v_cndmask_b32_e64 v22, v177, v22, s[30:31]
	v_add_f32_e32 v23, v87, v23
	v_cndmask_b32_e64 v23, v177, v23, s[36:37]
	v_add_f32_e32 v24, v88, v24
	v_cndmask_b32_e64 v24, v177, v24, s[40:41]
	v_add_f32_e32 v25, v89, v25
	v_cndmask_b32_e64 v25, v177, v25, s[44:45]
	v_add_f32_e32 v26, v90, v26
	v_cndmask_b32_e64 v26, v177, v26, s[48:49]
	v_add_f32_e32 v27, v91, v27
	v_cndmask_b32_e64 v27, v177, v27, s[52:53]
	v_add_f32_e32 v60, v92, v60
	v_cndmask_b32_e64 v60, v177, v60, s[56:57]
	v_add_f32_e32 v61, v93, v61
	v_cndmask_b32_e64 v61, v177, v61, s[60:61]
	v_add_f32_e32 v62, v94, v62
	v_cndmask_b32_e64 v62, v177, v62, s[64:65]
	v_add_f32_e32 v63, v95, v63
	v_cndmask_b32_e64 v63, v177, v63, s[68:69]
	ds_read_b32 v4, v179 offset:256
	ds_read_b32 v5, v179 offset:260
	ds_read_b32 v6, v179 offset:264
	ds_read_b32 v7, v179 offset:284
	ds_read_b32 v8, v179 offset:288
	ds_read_b32 v9, v179 offset:292
	ds_read_b32 v10, v179 offset:296
	ds_read_b32 v11, v179 offset:316
	ds_read_b32 v12, v179 offset:320
	ds_read_b32 v13, v179 offset:324
	ds_read_b32 v14, v179 offset:328
	ds_read_b32 v15, v179 offset:348
	ds_read_b32 v80, v179 offset:352
	ds_read_b32 v82, v179 offset:356
	ds_read_b32 v81, v179 offset:360
	s_waitcnt lgkmcnt(14)
	v_add_f32_e32 v0, v130, v0
	v_add_f32_e32 v4, v131, v4
	s_waitcnt lgkmcnt(13)
	v_add_f32_e32 v5, v132, v5
	s_waitcnt lgkmcnt(12)
	v_add_f32_e32 v6, v133, v6
	s_waitcnt lgkmcnt(2)
	v_add_f32_e32 v87, v143, v80
	v_cndmask_b32_e64 v80, v177, v0, s[8:9]
	v_max3_f32 v0, v16, v17, v80
	s_waitcnt lgkmcnt(1)
	v_add_f32_e32 v94, v144, v82
	s_waitcnt lgkmcnt(0)
	v_add_f32_e32 v128, v145, v81
	v_cndmask_b32_e64 v82, v177, v5, s[16:17]
	v_cndmask_b32_e64 v81, v177, v6, s[20:21]
	v_max3_f32 v0, v0, v82, v81
	v_cndmask_b32_e64 v95, v177, v4, s[12:13]
	v_max3_f32 v4, v18, v19, v95
	v_add_f32_e32 v7, v134, v7
	v_add_f32_e32 v8, v135, v8
	v_add_f32_e32 v9, v136, v9
	v_add_f32_e32 v10, v137, v10
	v_max3_f32 v0, v0, v20, v21
	v_max3_f32 v4, v4, v22, v23
	v_cndmask_b32_e64 v84, v177, v7, s[24:25]
	v_cndmask_b32_e64 v89, v177, v8, s[28:29]
	v_max3_f32 v0, v0, v84, v89
	v_cndmask_b32_e64 v86, v177, v9, s[34:35]
	v_cndmask_b32_e64 v83, v177, v10, s[38:39]
	v_max3_f32 v4, v4, v86, v83
	v_add_f32_e32 v11, v138, v11
	v_add_f32_e32 v12, v139, v12
	v_add_f32_e32 v13, v140, v13
	v_add_f32_e32 v14, v141, v14
	v_max3_f32 v0, v0, v24, v25
	v_max3_f32 v4, v4, v26, v27
	v_cndmask_b32_e64 v88, v177, v11, s[42:43]
	v_cndmask_b32_e64 v91, v177, v12, s[46:47]
	v_max3_f32 v0, v0, v88, v91
	v_cndmask_b32_e64 v90, v177, v13, s[50:51]
	v_cndmask_b32_e64 v85, v177, v14, s[54:55]
	v_max3_f32 v4, v4, v90, v85
	v_add_f32_e32 v15, v142, v15
	v_max3_f32 v0, v0, v60, v61
	v_max3_f32 v4, v4, v62, v63
	v_cndmask_b32_e64 v92, v177, v15, s[58:59]
	v_cndmask_b32_e64 v93, v177, v87, s[62:63]
	v_max3_f32 v0, v0, v92, v93
	v_cndmask_b32_e64 v94, v177, v94, s[66:67]
	v_cndmask_b32_e64 v87, v177, v128, s[70:71]
	v_max3_f32 v4, v4, v94, v87
	v_max_f32_e32 v0, v0, v4
	v_mov_b32_e32 v4, v0
	s_nop 1
	v_permlane32_swap_b32_e32 v0, v4
	v_max_f32_e32 v180, v0, v4
